# scan: hand-written step loop with quad-masked DPP y-reduction (43 instr per step), loader iteration reordered with global loads and no wait on the Y store, counted lgkmcnt
# speedup vs baseline: 1.0205x; 1.0205x over previous
; #define SC_GET(X, t) do { const float* p = rec + (t) * 320; w##X = *(const f32x4*)p; a##X = *(const f32x4*)(p + 4); b##X = *(const f32x4*)(p + 8); k##X = *(const f32x4*)(p + 12); q##X = *(const f32x4*)(p + 16); \
;                 v##X = *(const f32x4*)(VVa + (t) * 64); } while (0)
; DI void scan_phase(unsigned char* lds, const Ctx& a, const Op& d, const int variant) {
;     ...
;                 const float* base = (const float*)(lds + bi * SC_BUF);
;                 const float* rec = base + jg * 20; const float* VVa = base + 10240 + rA * 2;
;                 f32x4 wA, aA, bA, kA, qA, vA, wB, aB, bB, kB, qB, vB;
;     ...
;                 SC_GET(A, 0);
; #pragma unroll 2
;                 for (int t = 0; t < SC_T; t += 2) {
;                     SC_GET(B, t + 1);
;                     SC_STEP(A, t);
;                     if (t + 2 < SC_T) SC_GET(A, t + 2);
;                     SC_STEP(B, t + 1);
;                 }
.LBB0_453:
	s_and_b32 s48, s47, 1
	s_and_saveexec_b64 s[10:11], s[8:9]
	s_xor_b64 s[10:11], exec, s[10:11]
	s_cbranch_execz .LBB0_466
	s_mul_i32 s30, s48, 0xd000
	v_add_u32_e32 v175, s30, v157
	v_add_u32_e32 v123, s30, v158
	v_mbcnt_lo_u32_b32 v176, -1, 0
	v_mbcnt_hi_u32_b32 v176, -1, v176
	v_bfe_u32 v177, v176, 3, 1
	v_bfe_u32 v176, v176, 2, 1
	v_lshlrev_b32_e32 v177, 7, v177
	v_lshl_add_u32 v176, v176, 2, v177
	v_add3_u32 v178, v169, s30, v176
	v_cndmask_b32_e64 v176, 0, 1.0, s[4:5]
	v_mov_b32_e32 v177, v176
	s_mov_b32 s34, 0x11111111
	s_mov_b32 s35, 0x11111111
	ds_read_b128 v[40:43], v175
	ds_read_b128 v[44:47], v175 offset:16
	ds_read_b128 v[48:51], v175 offset:32
	ds_read_b128 v[52:55], v175 offset:48
	ds_read_b128 v[56:59], v175 offset:64
	ds_read_b128 v[60:63], v123 offset:40960
	s_mov_b32 s38, 8
	s_waitcnt lgkmcnt(0)
.Lscan_steps:
	s_waitcnt lgkmcnt(1)
	v_pk_mul_f32 v[106:107], v[64:65], v[44:45] op_sel_hi:[1,0]
	ds_read_b128 v[72:75], v175 offset:1280
	v_pk_mul_f32 v[108:109], v[64:65], v[56:57] op_sel_hi:[1,0]
	ds_read_b128 v[76:79], v175 offset:1296
	v_pk_fma_f32 v[106:107], v[66:67], v[44:45], v[106:107] op_sel:[0,1,0]
	ds_read_b128 v[80:83], v175 offset:1312
	v_pk_fma_f32 v[108:109], v[66:67], v[56:57], v[108:109] op_sel:[0,1,0]
	ds_read_b128 v[84:87], v175 offset:1328
	v_pk_fma_f32 v[106:107], v[68:69], v[46:47], v[106:107] op_sel_hi:[1,0,1]
	ds_read_b128 v[88:91], v175 offset:1344
	v_pk_fma_f32 v[108:109], v[68:69], v[58:59], v[108:109] op_sel_hi:[1,0,1]
	ds_read_b128 v[92:95], v123 offset:41216
	v_pk_fma_f32 v[106:107], v[70:71], v[46:47], v[106:107] op_sel:[0,1,0]
	v_swap_b32 v61, v62
	v_pk_fma_f32 v[108:109], v[70:71], v[58:59], v[108:109] op_sel:[0,1,0]
	v_pk_mul_f32 v[110:111], v[64:65], v[40:41] op_sel_hi:[1,0]
	v_add_f32_dpp v106, v106, v106 quad_perm:[1,0,3,2] row_mask:0xf bank_mask:0xf bound_ctrl:1
	v_add_f32_dpp v107, v107, v107 quad_perm:[1,0,3,2] row_mask:0xf bank_mask:0xf bound_ctrl:1
	v_pk_fma_f32 v[108:109], v[62:63], v[176:177], v[108:109]
	v_pk_mul_f32 v[112:113], v[66:67], v[40:41] op_sel:[0,1]
	v_add_f32_dpp v106, v106, v106 quad_perm:[2,3,0,1] row_mask:0xf bank_mask:0xf bound_ctrl:1
	v_add_f32_dpp v107, v107, v107 quad_perm:[2,3,0,1] row_mask:0xf bank_mask:0xf bound_ctrl:1
	v_add_f32_dpp v148, v108, v108 row_half_mirror row_mask:0xf bank_mask:0xf bound_ctrl:1
	v_add_f32_dpp v148, v109, v109 row_half_mirror row_mask:0xf bank_mask:0xa
	v_add_f32_dpp v106, v106, v106 row_half_mirror row_mask:0xf bank_mask:0xf bound_ctrl:1
	v_add_f32_dpp v107, v107, v107 row_half_mirror row_mask:0xf bank_mask:0xf bound_ctrl:1
	v_pk_mul_f32 v[144:145], v[68:69], v[42:43] op_sel_hi:[1,0]
	v_pk_mul_f32 v[146:147], v[70:71], v[42:43] op_sel:[0,1]
	v_add_f32_dpp v106, v106, v106 row_mirror row_mask:0xf bank_mask:0xf bound_ctrl:1
	v_add_f32_dpp v107, v107, v107 row_mirror row_mask:0xf bank_mask:0xf bound_ctrl:1
	v_pk_fma_f32 v[110:111], v[60:61], v[52:53], v[110:111] op_sel_hi:[1,0,1]
	v_pk_fma_f32 v[112:113], v[60:61], v[52:53], v[112:113] op_sel:[0,1,0]
	v_pk_fma_f32 v[144:145], v[60:61], v[54:55], v[144:145] op_sel_hi:[1,0,1]
	v_pk_fma_f32 v[146:147], v[60:61], v[54:55], v[146:147] op_sel:[0,1,0]
	v_pk_fma_f32 v[64:65], v[106:107], v[48:49], v[110:111] op_sel_hi:[1,0,1]
	v_pk_fma_f32 v[66:67], v[106:107], v[48:49], v[112:113] op_sel:[0,1,0]
	v_pk_fma_f32 v[68:69], v[106:107], v[50:51], v[144:145] op_sel_hi:[1,0,1]
	v_pk_fma_f32 v[70:71], v[106:107], v[50:51], v[146:147] op_sel:[0,1,0]
	s_waitcnt lgkmcnt(0)
	v_pk_mul_f32 v[106:107], v[64:65], v[76:77] op_sel_hi:[1,0]
	ds_read_b128 v[40:43], v175 offset:2560
	v_pk_mul_f32 v[108:109], v[64:65], v[88:89] op_sel_hi:[1,0]
	ds_read_b128 v[44:47], v175 offset:2576
	v_pk_fma_f32 v[106:107], v[66:67], v[76:77], v[106:107] op_sel:[0,1,0]
	ds_read_b128 v[48:51], v175 offset:2592
	v_pk_fma_f32 v[108:109], v[66:67], v[88:89], v[108:109] op_sel:[0,1,0]
	ds_read_b128 v[52:55], v175 offset:2608
	v_pk_fma_f32 v[106:107], v[68:69], v[78:79], v[106:107] op_sel_hi:[1,0,1]
	ds_read_b128 v[56:59], v175 offset:2624
	v_pk_fma_f32 v[108:109], v[68:69], v[90:91], v[108:109] op_sel_hi:[1,0,1]
	ds_read_b128 v[60:63], v123 offset:41472
	v_pk_fma_f32 v[106:107], v[70:71], v[78:79], v[106:107] op_sel:[0,1,0]
	v_swap_b32 v93, v94
	v_pk_fma_f32 v[108:109], v[70:71], v[90:91], v[108:109] op_sel:[0,1,0]
	v_pk_mul_f32 v[110:111], v[64:65], v[72:73] op_sel_hi:[1,0]
	v_add_f32_dpp v106, v106, v106 quad_perm:[1,0,3,2] row_mask:0xf bank_mask:0xf bound_ctrl:1
	v_add_f32_dpp v107, v107, v107 quad_perm:[1,0,3,2] row_mask:0xf bank_mask:0xf bound_ctrl:1
	v_pk_fma_f32 v[108:109], v[94:95], v[176:177], v[108:109]
	v_pk_mul_f32 v[112:113], v[66:67], v[72:73] op_sel:[0,1]
	v_add_f32_dpp v106, v106, v106 quad_perm:[2,3,0,1] row_mask:0xf bank_mask:0xf bound_ctrl:1
	v_add_f32_dpp v107, v107, v107 quad_perm:[2,3,0,1] row_mask:0xf bank_mask:0xf bound_ctrl:1
	v_add_f32_dpp v149, v108, v108 row_half_mirror row_mask:0xf bank_mask:0xf bound_ctrl:1
	v_add_f32_dpp v149, v109, v109 row_half_mirror row_mask:0xf bank_mask:0xa
	v_add_f32_dpp v106, v106, v106 row_half_mirror row_mask:0xf bank_mask:0xf bound_ctrl:1
	v_add_f32_dpp v107, v107, v107 row_half_mirror row_mask:0xf bank_mask:0xf bound_ctrl:1
	v_pk_mul_f32 v[144:145], v[68:69], v[74:75] op_sel_hi:[1,0]
	v_pk_mul_f32 v[146:147], v[70:71], v[74:75] op_sel:[0,1]
	v_add_f32_dpp v150, v148, v148 row_ror:8 row_mask:0xf bank_mask:0xf bound_ctrl:1
	v_add_f32_dpp v150, v149, v149 row_ror:8 row_mask:0xf bank_mask:0xc
	v_add_f32_dpp v106, v106, v106 row_mirror row_mask:0xf bank_mask:0xf bound_ctrl:1
	v_add_f32_dpp v107, v107, v107 row_mirror row_mask:0xf bank_mask:0xf bound_ctrl:1
	v_pk_fma_f32 v[110:111], v[92:93], v[84:85], v[110:111] op_sel_hi:[1,0,1]
	v_pk_fma_f32 v[112:113], v[92:93], v[84:85], v[112:113] op_sel:[0,1,0]
	v_pk_fma_f32 v[144:145], v[92:93], v[86:87], v[144:145] op_sel_hi:[1,0,1]
	v_pk_fma_f32 v[146:147], v[92:93], v[86:87], v[146:147] op_sel:[0,1,0]
	v_add_f32_dpp v150, v150, v150 quad_perm:[1,0,3,2] row_mask:0xf bank_mask:0xf bound_ctrl:1
	v_pk_fma_f32 v[64:65], v[106:107], v[80:81], v[110:111] op_sel_hi:[1,0,1]
	v_pk_fma_f32 v[66:67], v[106:107], v[80:81], v[112:113] op_sel:[0,1,0]
	v_add_f32_dpp v150, v150, v150 quad_perm:[2,3,0,1] row_mask:0xf bank_mask:0xf bound_ctrl:1
	v_pk_fma_f32 v[68:69], v[106:107], v[82:83], v[144:145] op_sel_hi:[1,0,1]
	v_pk_fma_f32 v[70:71], v[106:107], v[82:83], v[146:147] op_sel:[0,1,0]
	s_mov_b64 exec, s[34:35]
	ds_write_b32 v178, v150 offset:0
	s_mov_b64 exec, -1
	s_waitcnt lgkmcnt(1)
; #define SC_GET(X, t) do { const float* p = rec + (t) * 320; w##X = *(const f32x4*)p; a##X = *(const f32x4*)(p + 4); b##X = *(const f32x4*)(p + 8); k##X = *(const f32x4*)(p + 12); q##X = *(const f32x4*)(p + 16); \
;                 v##X = *(const f32x4*)(VVa + (t) * 64); } while (0)
; DI void scan_phase(unsigned char* lds, const Ctx& a, const Op& d, const int variant) {
;     ...
;                 SC_GET(A, 0);
; #pragma unroll 2
;                 for (int t = 0; t < SC_T; t += 2) {
;                     SC_GET(B, t + 1);
;                     SC_STEP(A, t);
;                     if (t + 2 < SC_T) SC_GET(A, t + 2);
;                     SC_STEP(B, t + 1);
;                 }
	v_pk_mul_f32 v[106:107], v[64:65], v[44:45] op_sel_hi:[1,0]
	ds_read_b128 v[72:75], v175 offset:3840
	v_pk_mul_f32 v[108:109], v[64:65], v[56:57] op_sel_hi:[1,0]
	ds_read_b128 v[76:79], v175 offset:3856
	v_pk_fma_f32 v[106:107], v[66:67], v[44:45], v[106:107] op_sel:[0,1,0]
	ds_read_b128 v[80:83], v175 offset:3872
	v_pk_fma_f32 v[108:109], v[66:67], v[56:57], v[108:109] op_sel:[0,1,0]
	ds_read_b128 v[84:87], v175 offset:3888
	v_pk_fma_f32 v[106:107], v[68:69], v[46:47], v[106:107] op_sel_hi:[1,0,1]
	ds_read_b128 v[88:91], v175 offset:3904
	v_pk_fma_f32 v[108:109], v[68:69], v[58:59], v[108:109] op_sel_hi:[1,0,1]
	ds_read_b128 v[92:95], v123 offset:41728
	v_pk_fma_f32 v[106:107], v[70:71], v[46:47], v[106:107] op_sel:[0,1,0]
	v_swap_b32 v61, v62
	v_pk_fma_f32 v[108:109], v[70:71], v[58:59], v[108:109] op_sel:[0,1,0]
	v_pk_mul_f32 v[110:111], v[64:65], v[40:41] op_sel_hi:[1,0]
	v_add_f32_dpp v106, v106, v106 quad_perm:[1,0,3,2] row_mask:0xf bank_mask:0xf bound_ctrl:1
	v_add_f32_dpp v107, v107, v107 quad_perm:[1,0,3,2] row_mask:0xf bank_mask:0xf bound_ctrl:1
	v_pk_fma_f32 v[108:109], v[62:63], v[176:177], v[108:109]
	v_pk_mul_f32 v[112:113], v[66:67], v[40:41] op_sel:[0,1]
	v_add_f32_dpp v106, v106, v106 quad_perm:[2,3,0,1] row_mask:0xf bank_mask:0xf bound_ctrl:1
	v_add_f32_dpp v107, v107, v107 quad_perm:[2,3,0,1] row_mask:0xf bank_mask:0xf bound_ctrl:1
	v_add_f32_dpp v148, v108, v108 row_half_mirror row_mask:0xf bank_mask:0xf bound_ctrl:1
	v_add_f32_dpp v148, v109, v109 row_half_mirror row_mask:0xf bank_mask:0xa
	v_add_f32_dpp v106, v106, v106 row_half_mirror row_mask:0xf bank_mask:0xf bound_ctrl:1
	v_add_f32_dpp v107, v107, v107 row_half_mirror row_mask:0xf bank_mask:0xf bound_ctrl:1
	v_pk_mul_f32 v[144:145], v[68:69], v[42:43] op_sel_hi:[1,0]
	v_pk_mul_f32 v[146:147], v[70:71], v[42:43] op_sel:[0,1]
	v_add_f32_dpp v106, v106, v106 row_mirror row_mask:0xf bank_mask:0xf bound_ctrl:1
	v_add_f32_dpp v107, v107, v107 row_mirror row_mask:0xf bank_mask:0xf bound_ctrl:1
	v_pk_fma_f32 v[110:111], v[60:61], v[52:53], v[110:111] op_sel_hi:[1,0,1]
	v_pk_fma_f32 v[112:113], v[60:61], v[52:53], v[112:113] op_sel:[0,1,0]
	v_pk_fma_f32 v[144:145], v[60:61], v[54:55], v[144:145] op_sel_hi:[1,0,1]
	v_pk_fma_f32 v[146:147], v[60:61], v[54:55], v[146:147] op_sel:[0,1,0]
	v_pk_fma_f32 v[64:65], v[106:107], v[48:49], v[110:111] op_sel_hi:[1,0,1]
	v_pk_fma_f32 v[66:67], v[106:107], v[48:49], v[112:113] op_sel:[0,1,0]
	v_pk_fma_f32 v[68:69], v[106:107], v[50:51], v[144:145] op_sel_hi:[1,0,1]
	v_pk_fma_f32 v[70:71], v[106:107], v[50:51], v[146:147] op_sel:[0,1,0]
	s_waitcnt lgkmcnt(0)
	v_pk_mul_f32 v[106:107], v[64:65], v[76:77] op_sel_hi:[1,0]
	ds_read_b128 v[40:43], v175 offset:5120
	v_pk_mul_f32 v[108:109], v[64:65], v[88:89] op_sel_hi:[1,0]
	ds_read_b128 v[44:47], v175 offset:5136
	v_pk_fma_f32 v[106:107], v[66:67], v[76:77], v[106:107] op_sel:[0,1,0]
	ds_read_b128 v[48:51], v175 offset:5152
	v_pk_fma_f32 v[108:109], v[66:67], v[88:89], v[108:109] op_sel:[0,1,0]
	ds_read_b128 v[52:55], v175 offset:5168
	v_pk_fma_f32 v[106:107], v[68:69], v[78:79], v[106:107] op_sel_hi:[1,0,1]
	ds_read_b128 v[56:59], v175 offset:5184
	v_pk_fma_f32 v[108:109], v[68:69], v[90:91], v[108:109] op_sel_hi:[1,0,1]
	ds_read_b128 v[60:63], v123 offset:41984
	v_pk_fma_f32 v[106:107], v[70:71], v[78:79], v[106:107] op_sel:[0,1,0]
	v_swap_b32 v93, v94
	v_pk_fma_f32 v[108:109], v[70:71], v[90:91], v[108:109] op_sel:[0,1,0]
	v_pk_mul_f32 v[110:111], v[64:65], v[72:73] op_sel_hi:[1,0]
	v_add_f32_dpp v106, v106, v106 quad_perm:[1,0,3,2] row_mask:0xf bank_mask:0xf bound_ctrl:1
	v_add_f32_dpp v107, v107, v107 quad_perm:[1,0,3,2] row_mask:0xf bank_mask:0xf bound_ctrl:1
	v_pk_fma_f32 v[108:109], v[94:95], v[176:177], v[108:109]
	v_pk_mul_f32 v[112:113], v[66:67], v[72:73] op_sel:[0,1]
	v_add_f32_dpp v106, v106, v106 quad_perm:[2,3,0,1] row_mask:0xf bank_mask:0xf bound_ctrl:1
	v_add_f32_dpp v107, v107, v107 quad_perm:[2,3,0,1] row_mask:0xf bank_mask:0xf bound_ctrl:1
	v_add_f32_dpp v149, v108, v108 row_half_mirror row_mask:0xf bank_mask:0xf bound_ctrl:1
	v_add_f32_dpp v149, v109, v109 row_half_mirror row_mask:0xf bank_mask:0xa
	v_add_f32_dpp v106, v106, v106 row_half_mirror row_mask:0xf bank_mask:0xf bound_ctrl:1
	v_add_f32_dpp v107, v107, v107 row_half_mirror row_mask:0xf bank_mask:0xf bound_ctrl:1
	v_pk_mul_f32 v[144:145], v[68:69], v[74:75] op_sel_hi:[1,0]
	v_pk_mul_f32 v[146:147], v[70:71], v[74:75] op_sel:[0,1]
	v_add_f32_dpp v150, v148, v148 row_ror:8 row_mask:0xf bank_mask:0xf bound_ctrl:1
	v_add_f32_dpp v150, v149, v149 row_ror:8 row_mask:0xf bank_mask:0xc
	v_add_f32_dpp v106, v106, v106 row_mirror row_mask:0xf bank_mask:0xf bound_ctrl:1
	v_add_f32_dpp v107, v107, v107 row_mirror row_mask:0xf bank_mask:0xf bound_ctrl:1
	v_pk_fma_f32 v[110:111], v[92:93], v[84:85], v[110:111] op_sel_hi:[1,0,1]
	v_pk_fma_f32 v[112:113], v[92:93], v[84:85], v[112:113] op_sel:[0,1,0]
	v_pk_fma_f32 v[144:145], v[92:93], v[86:87], v[144:145] op_sel_hi:[1,0,1]
	v_pk_fma_f32 v[146:147], v[92:93], v[86:87], v[146:147] op_sel:[0,1,0]
	v_add_f32_dpp v150, v150, v150 quad_perm:[1,0,3,2] row_mask:0xf bank_mask:0xf bound_ctrl:1
	v_pk_fma_f32 v[64:65], v[106:107], v[80:81], v[110:111] op_sel_hi:[1,0,1]
	v_pk_fma_f32 v[66:67], v[106:107], v[80:81], v[112:113] op_sel:[0,1,0]
	v_add_f32_dpp v150, v150, v150 quad_perm:[2,3,0,1] row_mask:0xf bank_mask:0xf bound_ctrl:1
	v_pk_fma_f32 v[68:69], v[106:107], v[82:83], v[144:145] op_sel_hi:[1,0,1]
	v_pk_fma_f32 v[70:71], v[106:107], v[82:83], v[146:147] op_sel:[0,1,0]
	s_mov_b64 exec, s[34:35]
	ds_write_b32 v178, v150 offset:256
	s_mov_b64 exec, -1
	v_add_u32_e32 v175, 0x1400, v175
	v_add_u32_e32 v123, 0x400, v123
	v_add_u32_e32 v178, 0x200, v178
	s_add_i32 s38, s38, -1
	s_cmp_lg_u32 s38, 0
	s_cbranch_scc1 .Lscan_steps

; #define SC_LOAD2(c) do { SC_LOAD(c, tl0, pr, pk, pv, pa, pd); SC_LOAD(c, tl0 + 16, pr2, pk2_, pv2, pa2, pd2); } while (0)
; #define SC_STORE2(bi) do { SC_STORE(bi, tl0, pr, pk, pv, pa, pd); SC_STORE(bi, tl0 + 16, pr2, pk2_, pv2, pa2, pd2); } while (0)
; #define SC_YOUT(c) do { const float* Ys = (const float*)(lds + ((c) & 1) * SC_BUF) + 12288; const int tt = ltid >> 3, e = (ltid & 7) * 4; \
;             *(f32x4*)(Y + (rowbase + (size_t)(c) * SC_T + tt) * DM + h * 64 + half * 32 + e) = *(const f32x4*)(Ys + tt * 32 + e); } while (0)
; DI void scan_phase(unsigned char* lds, const Ctx& a, const Op& d, const int variant) {
;     ...
;                 if (c > 0 && !(variant & 4)) SC_YOUT(c - 1);
;                 if (!(variant & 2)) {
;                 if (c + 1 < NCH) SC_STORE2(bi ^ 1);
;                 if (c + 2 < NCH) SC_LOAD2(c + 2);
.LBB0_479:
	s_or_b64 exec, exec, s[10:11]
	s_cmpk_gt_u32 s47, 0x7e
	s_cbranch_scc1 .Lscan_yout

; #define INP(a, i) inp_(a, i)
; #define SC_LOAD2(c) do { SC_LOAD(c, tl0, pr, pk, pv, pa, pd); SC_LOAD(c, tl0 + 16, pr2, pk2_, pv2, pa2, pd2); } while (0)
; #define SC_STORE2(bi) do { SC_STORE(bi, tl0, pr, pk, pv, pa, pd); SC_STORE(bi, tl0 + 16, pr2, pk2_, pv2, pa2, pd2); } while (0)
; #define SC_YOUT(c) do { const float* Ys = (const float*)(lds + ((c) & 1) * SC_BUF) + 12288; const int tt = ltid >> 3, e = (ltid & 7) * 4; \
;             *(f32x4*)(Y + (rowbase + (size_t)(c) * SC_T + tt) * DM + h * 64 + half * 32 + e) = *(const f32x4*)(Ys + tt * 32 + e); } while (0)
; DI void scan_phase(unsigned char* lds, const Ctx& a, const Op& d, const int variant) {
;     ...
;         __syncthreads();
;         if (is_loader) { SC_LOAD2(0); SC_STORE2(0); SC_LOAD2(1); }
;         __syncthreads();
;         for (int c = 0; c < NCH; ++c) {
;             const int bi = c & 1;
;             float* Yl = (float*)(lds + bi * SC_BUF) + 12288;
;             if (is_loader) {
;                 if ((c & cv_mask) == 0 && cv_item < cv_total) {
;                     const int lay = cv_item >> 14, it = cv_item & 16383; const int L = (ia == 0) ? lay : 3;
;                     if (it < 8192) tr_load(INP(a, 31) + (size_t)L * DM * DFF, DM, DFF, it, DFF / 32, lane, cvr);
;                     else tr_load(INP(a, 32) + (size_t)L * DM * DFF, DFF, DM, it - 8192, DM / 32, lane, cvr);
;                     cv_pend = cv_item; cv_item += a.G * 4;
;                 }
;                 if ((c & cv_mask) == 2 && cv_pend >= 0) {
;                     const int lay = cv_pend >> 14, it = cv_pend & 16383; const int L = (ia == 0) ? lay : 3;
;                     bf16_t* WB = (bf16_t*)(a.ws + (L == 1 ? WS_MLP2 : WS_MLP));
;                     if (it < 8192) tr_finish(WB, DM, cv_scr, it, DFF / 32, lane, cvr);
;                     else tr_finish(WB + (size_t)16 * E_M, DFF, cv_scr, it - 8192, DM / 32, lane, cvr);
;                     cv_pend = -1;
;                 }
;                 if (c > 0 && !(variant & 4)) SC_YOUT(c - 1);
;                 if (!(variant & 2)) {
;                 if (c + 1 < NCH) SC_STORE2(bi ^ 1);
;                 if (c + 2 < NCH) SC_LOAD2(c + 2);
.LBB0_487:
	s_or_b64 exec, exec, s[10:11]
	s_cmpk_gt_u32 s47, 0x7d
	s_cbranch_scc1 .Lscan_yout
	s_lshl_b32 s10, s47, 5
	s_add_i32 s10, s10, 64
	s_add_u32 s10, s26, s10
	s_addc_u32 s11, s27, 0
	v_mov_b32_e32 v41, s11
	v_or_b32_e32 v40, s10, v114
	v_lshlrev_b64 v[40:41], 11, v[40:41]
	v_or_b32_e32 v40, v40, v172
	v_lshlrev_b64 v[44:45], 1, v[40:41]
	v_lshl_add_u64 v[46:47], s[18:19], 0, v[44:45]
	v_lshl_add_u64 v[48:49], s[20:21], 0, v[44:45]
	v_lshl_add_u64 v[50:51], s[24:25], 0, v[44:45]
	v_lshl_add_u64 v[44:45], s[22:23], 0, v[44:45]
	s_waitcnt vmcnt(0)
	global_load_dwordx2 v[124:125], v[46:47], off
	global_load_dwordx2 v[126:127], v[48:49], off
	global_load_dwordx2 v[128:129], v[50:51], off
	global_load_dwordx2 v[130:131], v[44:45], off
	v_mov_b32_e32 v45, s11
	v_or_b32_e32 v44, s10, v116
	v_lshlrev_b64 v[44:45], 11, v[44:45]
	v_or_b32_e32 v44, v44, v172
	v_lshl_add_u64 v[40:41], v[40:41], 2, s[12:13]
	v_lshlrev_b64 v[46:47], 1, v[44:45]
	v_lshl_add_u64 v[48:49], s[18:19], 0, v[46:47]
	global_load_dwordx4 v[98:101], v[40:41], off
	global_load_dwordx2 v[132:133], v[48:49], off
	v_lshl_add_u64 v[40:41], s[20:21], 0, v[46:47]
	v_lshl_add_u64 v[48:49], s[24:25], 0, v[46:47]
	v_lshl_add_u64 v[46:47], s[22:23], 0, v[46:47]
	global_load_dwordx2 v[134:135], v[40:41], off
	global_load_dwordx2 v[136:137], v[48:49], off
	global_load_dwordx2 v[138:139], v[46:47], off
	v_lshl_add_u64 v[40:41], v[44:45], 2, s[12:13]
	global_load_dwordx4 v[102:105], v[40:41], off
.Lscan_yout:
	s_cmp_eq_u32 s47, 0
	s_cbranch_scc1 .LBB0_451
	s_add_i32 s52, s47, -1
	s_bitcmp1_b32 s52, 0
	s_cselect_b32 s10, 0xd000, 0
	v_add_u32_e32 v40, s10, v168
	ds_read_b128 v[44:47], v40 offset:49152
	s_lshl_b64 s[10:11], s[52:53], 18
	v_lshl_add_u64 v[40:41], v[142:143], 0, s[10:11]
	s_waitcnt lgkmcnt(0)
	global_store_dwordx4 v[40:41], v[44:47], off
	s_branch .LBB0_451
